# v20 + RG-LRU scan loop with batched LDS reads + GLA pre-pass items done by GLA and team workgroups only (HGRN2 workgroups, the critical long jobs, start at once)
# speedup vs baseline: 1.0128x; 1.0128x over previous
.LBB0_80:
	v_readlane_b32 s22, v248, 1
	v_readlane_b32 s23, v248, 2
	s_add_u32 s0, s22, 0x72d00000
	s_addc_u32 s1, s23, 0
	v_writelane_b32 v249, s0, 4
	v_readlane_b32 s24, v248, 7
	v_readlane_b32 s48, v248, 26
	v_writelane_b32 v249, s1, 5
	s_ashr_i32 s0, s24, 31
	v_readlane_b32 s50, v248, 28
	v_writelane_b32 v249, s0, 6
	v_readlane_b32 s51, v248, 29
	s_add_u32 s0, s50, 0x2000
	s_addc_u32 s1, s51, 0
	v_writelane_b32 v249, s0, 7
	s_cmpk_lg_i32 s24, 0x100
	v_readlane_b32 s13, v248, 43
	v_writelane_b32 v249, s1, 8
	s_cselect_b64 s[0:1], -1, 0
	v_writelane_b32 v249, s0, 9
	s_cmpk_lt_i32 s13, 0x1400
	v_readlane_b32 s21, v248, 0
	v_writelane_b32 v249, s1, 10
	s_cselect_b64 s[0:1], -1, 0
	v_writelane_b32 v249, s0, 11
	v_readlane_b32 s49, v248, 27
	v_mov_b32_e32 v34, 0
	v_writelane_b32 v249, s1, 12
	s_add_i32 s0, s13, 0x3c80
	s_add_u32 s9, s22, 0x24500000
	s_addc_u32 s12, s23, 0
	s_add_u32 s5, s22, 0x1e500000
	v_writelane_b32 v249, s0, 13
	s_addc_u32 s11, s23, 0
	s_add_i32 s0, s21, 0xffffff97
	s_cmpk_lt_u32 s0, 0x67
	s_cselect_b64 s[0:1], -1, 0
	v_writelane_b32 v249, s0, 14
	v_mov_b32_e32 v219, 1
	v_mov_b32_e32 v222, 0x358637bd
	v_writelane_b32 v249, s1, 15
	s_add_i32 s0, s13, 0xfffffcb8
	s_cmpk_lt_i32 s0, 0x1400
	s_cselect_b64 s[0:1], -1, 0
	v_writelane_b32 v249, s0, 16
	v_mov_b32_e32 v223, 0x260
	v_mov_b32_e32 v224, 0x3ecc95a3
	v_writelane_b32 v249, s1, 17
	s_add_i32 s0, s13, 0x3938
	v_writelane_b32 v249, s0, 18
	s_add_u32 s0, s22, 0x4200
	s_addc_u32 s1, s23, 0
	v_writelane_b32 v249, s0, 19
	v_mov_b32_e32 v225, 0x3e2aaaab
	v_mov_b64_e32 v[164:165], 0x969
	v_writelane_b32 v249, s1, 20
	s_add_u32 s0, s22, 0x4400
	s_addc_u32 s1, s23, 0
	v_writelane_b32 v249, s0, 21
	v_mov_b64_e32 v[166:167], 0x968
	v_mov_b32_e32 v226, 0x41b17218
	v_writelane_b32 v249, s1, 22
	s_add_u32 s0, s22, 0x4500
	s_addc_u32 s1, s23, 0
	v_writelane_b32 v249, s0, 23
	v_mov_b64_e32 v[168:169], 0x630
	v_mov_b64_e32 v[170:171], 0x62f
	v_writelane_b32 v249, s1, 24
	s_add_u32 s0, s22, 0x4600
	s_addc_u32 s1, s23, 0
	v_writelane_b32 v249, s0, 25
	v_mov_b32_e32 v227, 0x1e040
	v_mov_b32_e32 v228, 2
	v_writelane_b32 v249, s1, 26
	s_add_u32 s0, s22, 0x4700
	s_addc_u32 s1, s23, 0
	v_writelane_b32 v249, s0, 27
	v_mov_b32_e32 v230, 0x3000
	v_mov_b32_e32 v231, 0x7f800000
	v_writelane_b32 v249, s1, 28
	s_add_u32 s0, s22, 0x4800
	s_addc_u32 s1, s23, 0
	v_writelane_b32 v249, s0, 29
	v_readlane_b32 s52, v248, 30
	v_readlane_b32 s53, v248, 31
	v_writelane_b32 v249, s1, 30
	s_add_u32 s0, s22, 0x4900
	s_addc_u32 s1, s23, 0
	v_writelane_b32 v249, s0, 31
	v_readlane_b32 s54, v248, 32
	v_readlane_b32 s55, v248, 33
	v_writelane_b32 v249, s1, 32
	s_add_u32 s0, s22, 0x4a00
	s_addc_u32 s1, s23, 0
	v_writelane_b32 v249, s0, 33
	v_readlane_b32 s56, v248, 34
	v_readlane_b32 s57, v248, 35
	v_writelane_b32 v249, s1, 34
	s_add_u32 s0, s22, 0x4b00
	s_addc_u32 s1, s23, 0
	v_writelane_b32 v249, s0, 35
	v_readlane_b32 s58, v248, 36
	v_readlane_b32 s59, v248, 37
	v_writelane_b32 v249, s1, 36
	s_add_u32 s0, s22, 0x4c00
	s_addc_u32 s1, s23, 0
	v_writelane_b32 v249, s0, 37
	v_readlane_b32 s60, v248, 38
	v_readlane_b32 s61, v248, 39
	v_writelane_b32 v249, s1, 38
	s_add_u32 s0, s22, 0x4d00
	s_addc_u32 s1, s23, 0
	v_writelane_b32 v249, s0, 39
	v_readlane_b32 s62, v248, 40
	v_readlane_b32 s63, v248, 41
	v_writelane_b32 v249, s1, 40
	s_add_u32 s0, s22, 0x4e00
	s_addc_u32 s1, s23, 0
	v_writelane_b32 v249, s0, 41
	s_nop 1
	v_writelane_b32 v249, s1, 42
	s_add_u32 s0, s22, 0x4f00
	s_addc_u32 s1, s23, 0
	v_writelane_b32 v249, s0, 43
	s_nop 1
	v_writelane_b32 v249, s1, 44
	s_add_u32 s0, s22, 0x5000
	s_addc_u32 s1, s23, 0
	v_writelane_b32 v249, s0, 45
	s_nop 1
	v_writelane_b32 v249, s1, 46
	s_add_u32 s0, s22, 0x5100
	s_addc_u32 s1, s23, 0
	v_writelane_b32 v249, s0, 47
	s_nop 1
	v_writelane_b32 v249, s1, 48
	s_add_u32 s0, s22, 0x5200
	s_addc_u32 s1, s23, 0
	v_writelane_b32 v249, s0, 49
	s_nop 1
	v_writelane_b32 v249, s1, 50
	s_add_u32 s0, s22, 0x5300
	s_addc_u32 s1, s23, 0
	v_writelane_b32 v249, s0, 51
	s_cmp_eq_u32 s46, 15
	s_nop 0
	v_writelane_b32 v249, s1, 52
	s_cselect_b64 s[0:1], -1, 0
	v_writelane_b32 v249, s0, 53
	s_cmp_eq_u32 s46, 14
	s_nop 0
	v_writelane_b32 v249, s1, 54
	s_cselect_b64 s[0:1], -1, 0
	v_writelane_b32 v249, s0, 55
	s_cmp_eq_u32 s46, 13
	s_nop 0
	v_writelane_b32 v249, s1, 56
	s_cselect_b64 s[0:1], -1, 0
	v_writelane_b32 v249, s0, 57
	s_cmp_eq_u32 s46, 12
	s_nop 0
	v_writelane_b32 v249, s1, 58
	s_cselect_b64 s[0:1], -1, 0
	v_writelane_b32 v249, s0, 59
	s_cmp_eq_u32 s46, 11
	s_nop 0
	v_writelane_b32 v249, s1, 60
	s_cselect_b64 s[0:1], -1, 0
	v_writelane_b32 v249, s0, 61
	s_cmp_eq_u32 s46, 10
	s_nop 0
	v_writelane_b32 v249, s1, 62
	s_cselect_b64 s[0:1], -1, 0
	v_writelane_b32 v249, s0, 63
	s_cmp_eq_u32 s46, 9
	s_nop 0
	v_writelane_b32 v250, s1, 0
	s_cselect_b64 s[0:1], -1, 0
	v_writelane_b32 v250, s0, 1
	s_cmp_eq_u32 s46, 8
	s_nop 0
	v_writelane_b32 v250, s1, 2
	s_cselect_b64 s[0:1], -1, 0
	v_writelane_b32 v250, s0, 3
	s_cmp_eq_u32 s46, 7
	s_nop 0
	v_writelane_b32 v250, s1, 4
	s_cselect_b64 s[0:1], -1, 0
	v_writelane_b32 v250, s0, 5
	s_cmp_eq_u32 s46, 6
	s_nop 0
	v_writelane_b32 v250, s1, 6
	s_cselect_b64 s[0:1], -1, 0
	v_writelane_b32 v250, s0, 7
	s_cmp_eq_u32 s46, 5
	s_nop 0
	v_writelane_b32 v250, s1, 8
	s_cselect_b64 s[0:1], -1, 0
	v_writelane_b32 v250, s0, 9
	s_cmp_eq_u32 s46, 4
	s_nop 0
	v_writelane_b32 v250, s1, 10
	s_cselect_b64 s[0:1], -1, 0
	v_writelane_b32 v250, s0, 11
	s_cmp_eq_u32 s46, 3
	s_nop 0
	v_writelane_b32 v250, s1, 12
	s_cselect_b64 s[0:1], -1, 0
	v_writelane_b32 v250, s0, 13
	s_cmp_eq_u32 s46, 2
	s_nop 0
	v_writelane_b32 v250, s1, 14
	s_cselect_b64 s[0:1], -1, 0
	v_writelane_b32 v250, s0, 15
	s_cmp_eq_u32 s46, 1
	s_nop 0
	v_writelane_b32 v250, s1, 16
	s_cselect_b64 s[0:1], -1, 0
	v_writelane_b32 v250, s0, 17
	s_cmp_eq_u32 s46, 0
	s_nop 0
	v_writelane_b32 v250, s1, 18
	s_cselect_b64 s[0:1], -1, 0
	v_writelane_b32 v250, s0, 19
	s_nop 1
	v_writelane_b32 v250, s1, 20
	s_lshl_b32 s0, s46, 8
	s_add_u32 s0, s2, s0
	s_addc_u32 s1, s3, 0
	s_add_u32 s2, s0, 0x1400
	s_addc_u32 s3, s1, 0
	v_writelane_b32 v250, s2, 21
	s_add_u32 s0, s0, 0x2400
	s_addc_u32 s1, s1, 0
	v_writelane_b32 v250, s3, 22
	v_writelane_b32 v250, s0, 23
	s_nop 1
	v_writelane_b32 v250, s1, 24
	s_add_u32 s0, s22, 0x7400
	s_addc_u32 s1, s23, 0
	v_writelane_b32 v250, s0, 25
	s_nop 1
	v_writelane_b32 v250, s1, 26
	s_add_u32 s0, s22, 0x7500
	s_addc_u32 s1, s23, 0
	v_writelane_b32 v250, s0, 27
	s_cmpk_lt_i32 s21, 0x220
	s_nop 0
	v_writelane_b32 v250, s1, 28
	s_cselect_b64 s[0:1], -1, 0
	v_writelane_b32 v250, s0, 29
	s_ashr_i32 s14, s21, 31
	s_add_i32 s8, s21, 0xffffff40
	v_writelane_b32 v250, s1, 30
	s_lshr_b32 s0, s14, 26
	s_add_i32 s0, s21, s0
	s_ashr_i32 s7, s0, 6
	s_add_i32 s0, s24, 0xffffff40
	v_writelane_b32 v250, s0, 31
	s_sub_i32 s0, s21, 64
	s_cmpk_lt_i32 s21, 0x80
	s_cselect_b32 s25, s21, s0
	s_add_i32 s25, s21, 0xffffff80
	s_cmpk_lt_i32 s21, 0x40
	s_cselect_b32 s25, s21, s25
	s_cmpk_lt_i32 s25, 0x220
	v_writelane_b32 v250, s0, 32
	s_cselect_b64 s[0:1], -1, 0
	v_writelane_b32 v250, s0, 33
	s_nop 1
	v_writelane_b32 v250, s1, 34
	s_add_u32 s0, s22, 0x12000
	v_writelane_b32 v250, s0, 35
	s_addc_u32 s0, s23, 0
	v_writelane_b32 v250, s0, 36
	s_add_i32 s0, s21, 0xffffff80
	v_writelane_b32 v250, s0, 37
	s_add_i32 s0, s21, 1
	v_writelane_b32 v250, s0, 38
	s_sub_i32 s0, s21, 63
	v_writelane_b32 v250, s0, 39
	s_add_i32 s0, s21, 0xffffff81
	s_cmpk_gt_i32 s21, 0xbf
	v_writelane_b32 v250, s0, 40
	s_cselect_b64 s[0:1], -1, 0
	s_cmpk_eq_i32 s24, 0x100
	s_cselect_b64 s[26:27], -1, 0
	s_and_b64 s[2:3], s[26:27], exec
	s_movk_i32 s2, 0x200
	s_cselect_b32 s6, s2, 0x210
	s_movk_i32 s2, 0x2000
	s_cselect_b32 s2, s2, 0x2100
	v_writelane_b32 v250, s2, 41
	s_cselect_b32 s19, 32, 33
	s_cselect_b32 s10, 0xc80, 0
	s_and_b64 s[0:1], s[0:1], s[26:27]
	v_writelane_b32 v250, s0, 42
	s_nop 1
	v_writelane_b32 v250, s1, 43
	s_add_u32 s0, s22, 0x10000
	v_writelane_b32 v250, s0, 44
	s_addc_u32 s0, s23, 0
	v_writelane_b32 v250, s0, 45
	s_lshl_b32 s0, s8, 3
	s_add_i32 s15, s33, s0
	s_cmpk_lt_i32 s21, 0xf0
	s_mul_hi_i32 s0, s8, 0x55555556
	s_cselect_b64 s[2:3], -1, 0
	s_lshr_b32 s1, s0, 31
	s_add_i32 s1, s0, s1
	s_mul_i32 s0, s1, -3
	v_writelane_b32 v250, s2, 46
	s_add_i32 s0, s0, s8
	s_mul_i32 s4, s1, 0x300000
	v_writelane_b32 v250, s3, 47
	s_lshl_b32 s2, s0, 11
	s_ashr_i32 s3, s2, 31
	s_lshl_b64 s[28:29], s[2:3], 1
	s_add_u32 s2, s5, s28
	v_writelane_b32 v250, s5, 48
	s_addc_u32 s3, s11, s29
	v_writelane_b32 v250, s11, 49
	s_add_u32 s2, s2, s4
	s_mul_hi_i32 s5, s1, 0x300000
	v_writelane_b32 v250, s2, 50
	s_addc_u32 s2, s3, s5
	v_writelane_b32 v250, s2, 51
	s_lshl_b32 s1, s1, 8
	v_writelane_b32 v250, s1, 52
	s_ashr_i32 s1, s0, 31
	s_lshl_b64 s[2:3], s[0:1], 12
	v_writelane_b32 v250, s2, 53
	s_lshl_b64 s[0:1], s[0:1], 22
	s_ashr_i32 s8, s8, 2
	v_writelane_b32 v250, s3, 54
	v_writelane_b32 v250, s0, 55
	s_nop 1
	v_writelane_b32 v250, s1, 56
	s_and_b32 s0, s21, 3
	s_lshl_b32 s2, s0, 10
	s_lshl_b32 s30, s0, 11
	v_writelane_b32 v250, s9, 57
	s_add_u32 s11, s9, s30
	v_writelane_b32 v250, s12, 58
	s_addc_u32 s12, s12, 0
	s_ashr_i32 s9, s8, 31
	s_lshl_b32 s3, s0, 20
	s_lshl_b64 s[0:1], s[8:9], 21
	s_add_u32 s9, s11, s0
	v_writelane_b32 v250, s9, 59
	s_addc_u32 s9, s12, s1
	v_writelane_b32 v250, s9, 60
	s_lshl_b32 s8, s8, 8
	v_writelane_b32 v250, s8, 61
	s_cmpk_lt_i32 s15, 0xc80
	v_writelane_b32 v250, s15, 62
	s_cselect_b64 s[8:9], -1, 0
	v_writelane_b32 v250, s8, 63
	s_nop 1
	v_writelane_b32 v251, s9, 0
	s_add_u32 s8, s48, 0x1e040000
	s_addc_u32 s9, s49, 0
	v_writelane_b32 v251, s8, 1
	v_readlane_b32 s36, v248, 10
	v_readlane_b32 s50, v248, 24
	v_writelane_b32 v251, s9, 2
	s_add_u32 s8, s22, 0xf300000
	s_addc_u32 s9, s23, 0
	s_lshl_b32 s34, s19, 4
	v_writelane_b32 v251, s8, 3
	s_cmp_lt_i32 s21, s34
	v_readlane_b32 s51, v248, 25
	v_writelane_b32 v251, s9, 4
	s_cselect_b64 s[8:9], -1, 0
	v_writelane_b32 v251, s8, 5
	s_add_i32 s16, s24, s6
	s_add_i32 s20, s19, -8
	v_writelane_b32 v251, s9, 6
	s_lshr_b32 s8, s14, 29
	s_add_i32 s8, s21, s8
	v_writelane_b32 v251, s14, 7
	s_ashr_i32 s14, s8, 3
	s_and_b32 s8, s8, -8
	s_sub_i32 s15, s21, s8
	s_add_i32 s17, s16, -1
	s_add_i32 s8, s13, s10
	s_cmpk_lt_i32 s8, 0x3c80
	v_writelane_b32 v251, s8, 8
	s_cselect_b64 s[8:9], -1, 0
	v_writelane_b32 v251, s8, 9
	v_readlane_b32 s48, v248, 22
	v_readlane_b32 s49, v248, 23
	v_writelane_b32 v251, s9, 10
	s_add_u32 s8, s22, 0x85300000
	s_addc_u32 s9, s23, 0
	s_lshl_b32 s31, s19, 1
	v_writelane_b32 v251, s8, 11
	s_add_i32 s18, s10, s33
	s_or_b32 s33, s31, 1
	v_writelane_b32 v251, s9, 12
	s_add_u32 s8, s22, 0x76d00000
	v_writelane_b32 v251, s8, 13
	s_addc_u32 s8, s23, 0
	v_writelane_b32 v251, s8, 14
	s_add_u32 s8, s50, 0x4000
	s_addc_u32 s9, s51, 0
	v_writelane_b32 v251, s8, 15
	v_mov_b32_e32 v1, s15
	v_alignbit_b32 v1, s19, v1, 31
	v_writelane_b32 v251, s9, 16
	s_add_u32 s8, s48, 0x4000
	s_addc_u32 s9, s49, 0
	v_writelane_b32 v251, s8, 17
	v_readlane_b32 s37, v248, 11
	v_readlane_b32 s38, v248, 12
	v_writelane_b32 v251, s9, 18
	v_readlane_b32 s8, v248, 3
	v_readlane_b32 s9, v248, 4
	s_mov_b64 s[12:13], s[8:9]
	s_cmp_gt_i32 s12, 7
	v_readlane_b32 s10, v248, 5
	v_readlane_b32 s11, v248, 6
	s_cselect_b64 s[8:9], -1, 0
	s_cmp_lt_i32 s13, 9
	s_cselect_b64 s[10:11], -1, 0
	s_cmpk_lt_i32 s21, 0xc0
	s_cselect_b32 s7, s7, -1
	s_cmpk_gt_i32 s24, 0xc0
	s_cselect_b32 s7, s7, -2
	s_cmp_lt_i32 s7, 1
	s_cselect_b64 s[12:13], -1, 0
	v_writelane_b32 v251, s26, 19
	s_and_b64 s[12:13], s[26:27], s[12:13]
	s_cmp_lg_u32 s7, 1
	v_writelane_b32 v251, s27, 20
	v_writelane_b32 v251, s12, 21
	v_readlane_b32 s39, v248, 13
	v_readlane_b32 s40, v248, 14
	v_writelane_b32 v251, s13, 22
	v_writelane_b32 v251, s7, 23
	v_readfirstlane_b32 s7, v1
	v_writelane_b32 v251, s19, 24
	s_mul_i32 s7, s7, s15
	s_cselect_b64 s[12:13], -1, 0
	v_writelane_b32 v251, s12, 25
	s_add_i32 s7, s7, s14
	v_readlane_b32 s41, v248, 15
	v_writelane_b32 v251, s13, 26
	s_ashr_i32 s12, s7, 31
	s_lshr_b32 s12, s12, 25
	s_add_i32 s12, s7, s12
	s_ashr_i32 s12, s12, 7
	s_lshl_b32 s13, s12, 7
	s_sub_i32 s7, s7, s13
	s_lshl_b32 s12, s12, 3
	s_cmp_gt_i32 s12, s20
	s_cselect_b32 s13, 1, 8
	s_cmp_lt_i32 s15, 0
	s_cselect_b32 s19, s33, s31
	s_mul_i32 s15, s19, s15
	s_add_i32 s14, s15, s14
	v_cvt_f32_ubyte0_e32 v1, s13
	s_ashr_i32 s15, s14, 31
	v_rcp_iflag_f32_e32 v1, v1
	s_lshr_b32 s15, s15, 25
	s_add_i32 s15, s14, s15
	s_ashr_i32 s15, s15, 7
	s_lshl_b32 s19, s15, 7
	v_mul_f32_e32 v1, 0x4f7ffffe, v1
	v_writelane_b32 v251, s31, 27
	s_sub_i32 s14, s14, s19
	s_lshl_b32 s15, s15, 3
	v_cvt_u32_f32_e32 v1, v1
	v_writelane_b32 v251, s33, 28
	s_cmp_gt_i32 s15, s20
	v_writelane_b32 v251, s20, 29
	s_cselect_b32 s19, 1, 8
	s_or_b64 s[8:9], s[8:9], s[10:11]
	v_writelane_b32 v251, s8, 30
	s_mov_b32 s33, 0xbcf5c28f
	v_readlane_b32 s42, v248, 16
	v_writelane_b32 v251, s9, 31
	s_sub_i32 s8, 0, s13
	v_readfirstlane_b32 s9, v1
	s_mul_i32 s8, s8, s9
	s_mul_hi_u32 s8, s9, s8
	s_add_i32 s9, s9, s8
	s_abs_i32 s8, s7
	s_mul_hi_u32 s9, s8, s9
	s_mul_i32 s10, s9, s13
	s_sub_i32 s8, s8, s10
	s_ashr_i32 s10, s7, 31
	s_add_i32 s11, s9, 1
	s_sub_i32 s20, s8, s13
	s_cmp_ge_u32 s8, s13
	s_cselect_b32 s9, s11, s9
	s_cselect_b32 s8, s20, s8
	s_add_i32 s11, s9, 1
	s_cmp_ge_u32 s8, s13
	s_cselect_b32 s8, s11, s9
	s_xor_b32 s8, s8, s10
	s_sub_i32 s8, s8, s10
	v_writelane_b32 v251, s8, 32
	s_mul_i32 s8, s8, s13
	s_sub_i32 s7, s7, s8
	s_add_i32 s7, s12, s7
	v_writelane_b32 v251, s7, 33
	s_abs_i32 s7, s24
	v_cvt_f32_u32_e32 v1, s7
	s_sub_i32 s8, 0, s7
	v_readlane_b32 s43, v248, 17
	v_readlane_b32 s44, v248, 18
	v_rcp_iflag_f32_e32 v1, v1
	v_readlane_b32 s45, v248, 19
	v_readlane_b32 s46, v248, 20
	v_readlane_b32 s47, v248, 21
	v_mul_f32_e32 v1, 0x4f7ffffe, v1
	v_cvt_u32_f32_e32 v1, v1
	s_nop 0
	v_readfirstlane_b32 s9, v1
	s_mul_i32 s8, s8, s9
	s_mul_hi_u32 s8, s9, s8
	s_add_i32 s9, s9, s8
	s_sub_i32 s8, 1, s16
	s_max_i32 s8, s17, s8
	s_mul_hi_u32 s9, s8, s9
	s_mul_i32 s10, s9, s7
	s_sub_i32 s8, s8, s10
	s_xor_b32 s10, s17, s24
	s_ashr_i32 s10, s10, 31
	s_add_i32 s11, s9, 1
	s_sub_i32 s12, s8, s7
	s_cmp_ge_u32 s8, s7
	s_cselect_b32 s9, s11, s9
	s_cselect_b32 s8, s12, s8
	s_add_i32 s11, s9, 1
	s_cmp_ge_u32 s8, s7
	s_cselect_b32 s7, s11, s9
	s_xor_b32 s7, s7, s10
	s_not_b32 s8, s10
	s_add_i32 s7, s8, s7
	s_mul_i32 s7, s7, s24
	s_sub_i32 s6, s6, s7
	s_sub_i32 s7, s24, s6
	v_cvt_f32_ubyte0_e32 v1, s19
	s_cmp_lt_i32 s7, 1
	v_rcp_iflag_f32_e32 v1, v1
	s_cselect_b64 s[8:9], -1, 0
	v_writelane_b32 v251, s8, 34
	s_cmp_ge_i32 s21, s6
	v_mul_f32_e32 v1, 0x4f7ffffe, v1
	v_writelane_b32 v251, s9, 35
	s_cselect_b64 s[8:9], -1, 0
	s_sub_i32 s6, s21, s6
	v_writelane_b32 v251, s8, 36
	s_lshl_b32 s6, s6, 3
	s_add_i32 s6, s18, s6
	v_writelane_b32 v251, s9, 37
	s_lshl_b32 s7, s7, 3
	v_cvt_u32_f32_e32 v1, v1
	v_writelane_b32 v251, s7, 38
	s_cmpk_lt_i32 s6, 0x3c80
	v_writelane_b32 v251, s6, 39
	s_cselect_b64 s[6:7], -1, 0
	v_writelane_b32 v251, s6, 40
	s_nop 1
	v_writelane_b32 v251, s7, 41
	s_sub_i32 s6, 0, s19
	v_readfirstlane_b32 s7, v1
	s_mul_i32 s6, s6, s7
	s_mul_hi_u32 s6, s7, s6
	s_add_i32 s7, s7, s6
	s_abs_i32 s6, s14
	s_mul_hi_u32 s7, s6, s7
	s_mul_i32 s8, s7, s19
	s_sub_i32 s6, s6, s8
	s_ashr_i32 s8, s14, 31
	s_add_i32 s9, s7, 1
	s_sub_i32 s10, s6, s19
	s_cmp_ge_u32 s6, s19
	s_cselect_b32 s7, s9, s7
	s_cselect_b32 s6, s10, s6
	s_add_i32 s9, s7, 1
	s_cmp_ge_u32 s6, s19
	s_cselect_b32 s6, s9, s7
	s_xor_b32 s6, s6, s8
	s_sub_i32 s8, s6, s8
	s_mul_i32 s6, s8, s19
	s_sub_i32 s6, s14, s6
	s_add_i32 s10, s15, s6
	s_lshl_b32 s6, s21, 8
	v_writelane_b32 v251, s6, 42
	s_lshl_b32 s6, s24, 8
	v_writelane_b32 v251, s6, 43
	v_writelane_b32 v251, s25, 44
	s_lshl_b32 s6, s25, 8
	v_writelane_b32 v251, s6, 45
	s_mov_b32 s6, s10
	s_ashr_i32 s11, s10, 31
	v_writelane_b32 v251, s6, 46
	s_ashr_i32 s9, s8, 31
	v_mbcnt_lo_u32_b32 v1, -1, 0
	v_writelane_b32 v251, s7, 47
	s_lshl_b64 s[6:7], s[10:11], 21
	v_writelane_b32 v251, s6, 48
	v_mbcnt_hi_u32_b32 v229, -1, v1
	s_nop 0
	v_writelane_b32 v251, s7, 49
	s_mov_b32 s6, s8
	v_writelane_b32 v251, s6, 50
	s_nop 1
	v_writelane_b32 v251, s7, 51
	s_lshl_b64 s[6:7], s[8:9], 21
	s_add_u32 s4, s4, s28
	s_addc_u32 s5, s5, s29
	s_add_u32 s4, s22, s4
	v_writelane_b32 v251, s6, 52
	s_addc_u32 s5, s23, s5
	s_add_u32 s4, s4, 0x1e500100
	v_writelane_b32 v251, s7, 53
	v_writelane_b32 v251, s4, 54
	s_addc_u32 s4, s5, 0
	v_writelane_b32 v251, s4, 55
	s_add_u32 s4, s28, 0x55b80080
	v_writelane_b32 v251, s4, 56
	v_writelane_b32 v251, s28, 57
	s_addc_u32 s4, s29, 0
	s_or_b32 s0, s0, s30
	v_writelane_b32 v251, s29, 58
	s_mov_b32 s5, 0
	v_writelane_b32 v251, s4, 59
	s_add_u32 s0, s22, s0
	s_mov_b32 s35, s5
	s_addc_u32 s1, s23, s1
	v_writelane_b32 v251, s34, 60
	s_add_u32 s0, s0, 0x24500100
	s_mov_b64 s[6:7], -1
	v_writelane_b32 v251, s35, 61
	v_writelane_b32 v251, s0, 62
	s_addc_u32 s0, s1, 0
	v_writelane_b32 v251, s0, 63
	s_mul_hi_i32 s1, s66, 0x3000
	s_mul_i32 s0, s66, 0x3000
	v_writelane_b32 v252, s0, 0
	s_ashr_i32 s67, s66, 31
	s_mov_b32 s12, s5
	v_writelane_b32 v252, s1, 1
	s_lshl_b32 s0, s2, 1
	v_writelane_b32 v252, s0, 2
	s_lshl_b32 s0, s3, 2
	v_writelane_b32 v252, s0, 3
	v_writelane_b32 v252, s30, 4
	s_or_b32 s0, s30, 0x6a800080
	v_writelane_b32 v252, s0, 5
	s_add_i32 s0, 0, 0x19800
	v_writelane_b32 v252, s0, 6
	v_cmp_eq_u32_e64 s[0:1], 0, v0
	s_mov_b64 s[2:3], 0x80
	s_nop 0
	v_writelane_b32 v252, s0, 7
	s_nop 1
	v_writelane_b32 v252, s1, 8
	s_lshl_b64 s[0:1], s[66:67], 12
	v_writelane_b32 v252, s0, 9
	s_nop 1
	v_writelane_b32 v252, s1, 10
	s_lshl_b64 s[0:1], s[66:67], 7
	v_writelane_b32 v252, s0, 11
	s_nop 1
	v_writelane_b32 v252, s1, 12
	s_lshl_b64 s[0:1], s[66:67], 13
	v_writelane_b32 v252, s0, 13
	s_nop 1
	v_writelane_b32 v252, s1, 14
	s_mov_b32 s1, 0
	v_writelane_b32 v252, s0, 15
	s_nop 1
	v_writelane_b32 v252, s1, 16
	v_writelane_b32 v252, s66, 17
	s_nop 1
	v_writelane_b32 v252, s67, 18
	s_branch .LBB0_84

.LBB0_524:
	v_readlane_b32 s1, v254, 23
	s_add_i32 s0, s1, 0x80
	s_add_i32 s51, s51, 0x8000
	s_cmpk_gt_i32 s1, 0x19f
	s_waitcnt lgkmcnt(0)
	s_barrier
	s_cbranch_scc1 .LBB0_595

.LBB0_602:
	global_load_dword v1, v34, s[0:1] sc1
	s_movk_i32 s6, 0x7f
	s_waitcnt vmcnt(0)
	v_cmp_lt_u32_e32 vcc, s6, v1
	s_mov_b64 s[6:7], -1
	s_cbranch_vccnz .LBB0_601
	s_cmp_lg_u32 s8, 0
	s_sleep 2
	s_cbranch_scc0 .LBB0_600
	global_load_dword v1, v34, s[0:1] sc1
	s_movk_i32 s6, 0x80
	s_waitcnt vmcnt(0)
	v_cmp_gt_u32_e32 vcc, s6, v1
	s_mov_b64 s[6:7], -1
	s_cbranch_vccz .LBB0_601
	s_sleep 2
	global_load_dword v1, v34, s[0:1] sc1
	s_movk_i32 s6, 0x80
	s_waitcnt vmcnt(0)
	v_cmp_gt_u32_e32 vcc, s6, v1
	s_mov_b64 s[6:7], -1
	s_cbranch_vccz .LBB0_601
	s_sleep 2
	global_load_dword v1, v34, s[0:1] sc1
	s_movk_i32 s6, 0x80
	s_waitcnt vmcnt(0)
	v_cmp_gt_u32_e32 vcc, s6, v1
	s_mov_b64 s[6:7], -1
	s_cbranch_vccz .LBB0_601
	s_sleep 2
	global_load_dword v1, v34, s[0:1] sc1
	s_movk_i32 s6, 0x80
	s_waitcnt vmcnt(0)
	v_cmp_gt_u32_e32 vcc, s6, v1
	s_mov_b64 s[6:7], -1
	s_cbranch_vccz .LBB0_601
	s_sleep 2
	global_load_dword v1, v34, s[0:1] sc1
	s_movk_i32 s6, 0x80
	s_waitcnt vmcnt(0)
	v_cmp_gt_u32_e32 vcc, s6, v1
	s_mov_b64 s[6:7], -1
	s_cbranch_vccz .LBB0_601
	s_sleep 2
	global_load_dword v1, v34, s[0:1] sc1
	s_movk_i32 s6, 0x80
	s_waitcnt vmcnt(0)
	v_cmp_gt_u32_e32 vcc, s6, v1
	s_mov_b64 s[6:7], -1
	s_cbranch_vccz .LBB0_601
	s_sleep 2
	global_load_dword v1, v34, s[0:1] sc1
	s_movk_i32 s6, 0x80
	s_waitcnt vmcnt(0)
	v_cmp_gt_u32_e32 vcc, s6, v1
	s_mov_b64 s[6:7], -1
	s_cbranch_vccz .LBB0_601
	s_sleep 2
	s_add_i32 s8, s8, -8
	s_mov_b64 s[6:7], 0
	s_branch .LBB0_601
